# gate_up epilogue: 24 adjacent scalar f32 multiply pairs merged into v_pk_mul_f32 with broadcast row scale (same f32 math, fewer VALU issues)
# baseline (speedup 1.0000x reference)
.LBB0_946:
	s_min_u32 s4, s85, 32
	s_sub_i32 s5, 32, s4
	v_pk_mul_f32 v[122:123], v[126:127], v[122:123]
	v_pk_mul_f32 v[124:125], v[128:129], v[124:125]
	v_pk_mul_f32 v[114:115], v[118:119], v[114:115]
	v_lshl_or_b32 v176, s16, 7, v179
	v_readlane_b32 s16, v252, 0
	v_pk_mul_f32 v[116:117], v[120:121], v[116:117]
	v_readlane_b32 s17, v252, 1
	v_ashrrev_i32_e32 v177, 31, v176
	v_pk_mul_f32 v[112:113], v[108:109], v[112:113]
	v_pk_mul_f32 v[104:105], v[100:101], v[104:105]
	v_pk_mul_f32 v[96:97], v[92:93], v[96:97]
	v_pk_mul_f32 v[88:89], v[84:85], v[88:89]
	v_pk_mul_f32 v[80:81], v[76:77], v[80:81]
	v_pk_mul_f32 v[72:73], v[68:69], v[72:73]
	v_pk_mul_f32 v[64:65], v[60:61], v[64:65]
	v_add_u32_e32 v143, 0x80, v142
	v_pk_mul_f32 v[56:57], v[52:53], v[56:57]
	v_pk_mul_f32 v[48:49], v[44:45], v[48:49]
	v_pk_mul_f32 v[40:41], v[36:37], v[40:41]
	v_pk_mul_f32 v[32:33], v[28:29], v[32:33]
	v_pk_mul_f32 v[24:25], v[20:21], v[24:25]
	v_pk_mul_f32 v[0:1], v[4:5], v[0:1]
	v_pk_mul_f32 v[16:17], v[12:13], v[16:17]
	v_pk_mul_f32 v[2:3], v[6:7], v[2:3]
	s_andn2_b64 vcc, exec, s[38:39]
	s_waitcnt vmcnt(0)
	v_mov_b32_e32 v8, v191
	v_lshlrev_b64 v[192:193], s4, v[8:9]
	v_min_u32_e32 v8, 1, v192
	v_or_b32_e32 v8, v193, v8
	v_cvt_f32_u32_e32 v8, v8
	v_cvt_f32_u32_e32 v154, v190
	v_ldexp_f32 v8, v8, s5
	v_fmac_f32_e32 v8, 0x2f800000, v154
	v_fmamk_f32 v8, v8, 0x3a000000, v183
	v_rsq_f32_e32 v154, v8
	s_nop 0
	v_mul_f32_e32 v8, v154, v154
	v_mul_f32_e32 v154, 0xbfb8aa3b, v154
	v_mul_f32_e32 v155, v126, v154
	v_exp_f32_e32 v155, v155
	s_nop 0
	v_add_f32_e32 v155, 1.0, v155
	v_rcp_f32_e32 v190, v155
	v_mul_f32_e32 v155, v127, v154
	v_exp_f32_e32 v155, v155
	s_nop 0
	v_add_f32_e32 v155, 1.0, v155
	v_rcp_f32_e32 v191, v155
	s_nop 0
	v_pk_mul_f32 v[126:127], v[8:9], v[190:191] op_sel_hi:[0,1]
	v_pk_mul_f32 v[122:123], v[122:123], v[126:127]
	v_pk_mul_f32 v[126:127], v[128:129], v[154:155] op_sel_hi:[1,0]
	v_exp_f32_e32 v126, v126
	v_exp_f32_e32 v127, v127
	v_add_f32_e32 v126, 1.0, v126
	v_add_f32_e32 v127, 1.0, v127
	v_rcp_f32_e32 v126, v126
	v_rcp_f32_e32 v127, v127
	s_nop 0
	v_pk_mul_f32 v[126:127], v[8:9], v[126:127] op_sel_hi:[0,1]
	v_pk_mul_f32 v[124:125], v[124:125], v[126:127]
	v_pk_mul_f32 v[126:127], v[118:119], v[154:155] op_sel_hi:[1,0]
	v_exp_f32_e32 v126, v126
	v_exp_f32_e32 v127, v127
	v_add_f32_e32 v126, 1.0, v126
	v_add_f32_e32 v127, 1.0, v127
	v_rcp_f32_e32 v126, v126
	v_rcp_f32_e32 v127, v127
	s_nop 0
	v_pk_mul_f32 v[118:119], v[8:9], v[126:127] op_sel_hi:[0,1]
	v_pk_mul_f32 v[114:115], v[114:115], v[118:119]
	v_pk_mul_f32 v[118:119], v[120:121], v[154:155] op_sel_hi:[1,0]
	v_exp_f32_e32 v118, v118
	v_exp_f32_e32 v119, v119
	v_cvt_pk_bf16_f32 v120, v114, v115
	v_mov_b64_e32 v[114:115], s[16:17]
	v_add_f32_e32 v118, 1.0, v118
	v_add_f32_e32 v119, 1.0, v119
	v_rcp_f32_e32 v118, v118
	v_rcp_f32_e32 v119, v119
	s_nop 0
	v_pk_mul_f32 v[118:119], v[8:9], v[118:119] op_sel_hi:[0,1]
	v_pk_mul_f32 v[116:117], v[116:117], v[118:119]
	v_cvt_pk_bf16_f32 v118, v122, v123
	v_cvt_pk_bf16_f32 v121, v116, v117
	v_mad_i64_i32 v[122:123], s[16:17], v142, s66, v[114:115]
	v_lshlrev_b64 v[116:117], 1, v[176:177]
	v_cvt_pk_bf16_f32 v119, v124, v125
	v_lshl_add_u64 v[122:123], v[122:123], 0, v[116:117]
	v_mov_b32_e32 v8, v175
	global_store_dwordx4 v[122:123], v[118:121], off
	s_nop 1
	v_lshlrev_b64 v[118:119], s4, v[8:9]
	v_min_u32_e32 v8, 1, v118
	v_or_b32_e32 v8, v119, v8
	v_cvt_f32_u32_e32 v8, v8
	v_cvt_f32_u32_e32 v118, v174
	v_ldexp_f32 v8, v8, s5
	v_fmac_f32_e32 v8, 0x2f800000, v118
	v_fmamk_f32 v8, v8, 0x3a000000, v183
	v_rsq_f32_e32 v118, v8
	s_nop 0
	v_mul_f32_e32 v8, v118, v118
	v_mul_f32_e32 v118, 0xbfb8aa3b, v118
	v_mul_f32_e32 v119, v106, v118
	v_exp_f32_e32 v119, v119
	v_pk_mul_f32 v[108:109], v[108:109], v[118:119] op_sel_hi:[1,0]
	v_exp_f32_e32 v108, v108
	v_add_f32_e32 v119, 1.0, v119
	v_rcp_f32_e32 v120, v119
	v_mul_f32_e32 v119, v107, v118
	v_exp_f32_e32 v119, v119
	v_pk_mul_f32 v[106:107], v[106:107], v[110:111]
	v_exp_f32_e32 v109, v109
	v_add_f32_e32 v108, 1.0, v108
	v_add_f32_e32 v119, 1.0, v119
	v_rcp_f32_e32 v121, v119
	v_add_f32_e32 v109, 1.0, v109
	v_rcp_f32_e32 v108, v108
	v_rcp_f32_e32 v109, v109
	v_pk_mul_f32 v[110:111], v[8:9], v[120:121] op_sel_hi:[0,1]
	v_pk_mul_f32 v[106:107], v[106:107], v[110:111]
	v_pk_mul_f32 v[110:111], v[98:99], v[118:119] op_sel_hi:[1,0]
	v_exp_f32_e32 v110, v110
	v_exp_f32_e32 v111, v111
	v_pk_mul_f32 v[98:99], v[98:99], v[102:103]
	v_pk_mul_f32 v[108:109], v[8:9], v[108:109] op_sel_hi:[0,1]
	v_add_f32_e32 v110, 1.0, v110
	v_add_f32_e32 v111, 1.0, v111
	v_rcp_f32_e32 v110, v110
	v_rcp_f32_e32 v111, v111
	v_pk_mul_f32 v[108:109], v[112:113], v[108:109]
	v_pk_mul_f32 v[102:103], v[8:9], v[110:111] op_sel_hi:[0,1]
	v_pk_mul_f32 v[102:103], v[98:99], v[102:103]
	v_pk_mul_f32 v[98:99], v[100:101], v[118:119] op_sel_hi:[1,0]
	v_exp_f32_e32 v98, v98
	v_exp_f32_e32 v99, v99
	v_cvt_pk_bf16_f32 v100, v102, v103
	v_add_f32_e32 v98, 1.0, v98
	v_add_f32_e32 v99, 1.0, v99
	v_rcp_f32_e32 v98, v98
	v_rcp_f32_e32 v99, v99
	s_nop 0
	v_pk_mul_f32 v[98:99], v[8:9], v[98:99] op_sel_hi:[0,1]
	v_or_b32_e32 v8, 16, v142
	v_pk_mul_f32 v[104:105], v[104:105], v[98:99]
	v_mad_i64_i32 v[102:103], s[16:17], v8, s66, v[114:115]
	v_cvt_pk_bf16_f32 v98, v106, v107
	v_cvt_pk_bf16_f32 v99, v108, v109
	v_cvt_pk_bf16_f32 v101, v104, v105
	v_lshl_add_u64 v[102:103], v[102:103], 0, v[116:117]
	v_mov_b32_e32 v8, v173
	global_store_dwordx4 v[102:103], v[98:101], off
	s_nop 1
	v_lshlrev_b64 v[98:99], s4, v[8:9]
	v_min_u32_e32 v8, 1, v98
	v_or_b32_e32 v8, v99, v8
	v_cvt_f32_u32_e32 v8, v8
	v_cvt_f32_u32_e32 v98, v172
	v_ldexp_f32 v8, v8, s5
	v_fmac_f32_e32 v8, 0x2f800000, v98
	v_fmamk_f32 v8, v8, 0x3a000000, v183
	v_rsq_f32_e32 v98, v8
	s_nop 0
	v_mul_f32_e32 v100, 0xbfb8aa3b, v98
	v_mul_f32_e32 v8, v98, v98
	v_pk_mul_f32 v[98:99], v[90:91], v[100:101] op_sel_hi:[1,0]
	v_exp_f32_e32 v98, v98
	v_exp_f32_e32 v99, v99
	v_pk_mul_f32 v[90:91], v[90:91], v[94:95]
	v_mul_f32_e32 v92, v92, v100
	v_add_f32_e32 v98, 1.0, v98
	v_add_f32_e32 v99, 1.0, v99
	v_rcp_f32_e32 v98, v98
	v_rcp_f32_e32 v99, v99
	v_mul_f32_e32 v93, v93, v100
	v_exp_f32_e32 v92, v92
	v_exp_f32_e32 v93, v93
	v_pk_mul_f32 v[94:95], v[8:9], v[98:99] op_sel_hi:[0,1]
	v_pk_mul_f32 v[90:91], v[90:91], v[94:95]
	v_pk_mul_f32 v[94:95], v[82:83], v[100:101] op_sel_hi:[1,0]
	v_exp_f32_e32 v94, v94
	v_exp_f32_e32 v95, v95
	v_pk_mul_f32 v[82:83], v[82:83], v[86:87]
	v_add_f32_e32 v92, 1.0, v92
	v_add_f32_e32 v94, 1.0, v94
	v_add_f32_e32 v95, 1.0, v95
	v_rcp_f32_e32 v94, v94
	v_rcp_f32_e32 v95, v95
	v_add_f32_e32 v93, 1.0, v93
	v_rcp_f32_e32 v92, v92
	v_rcp_f32_e32 v93, v93
	v_pk_mul_f32 v[86:87], v[8:9], v[94:95] op_sel_hi:[0,1]
	v_pk_mul_f32 v[86:87], v[82:83], v[86:87]
	v_pk_mul_f32 v[82:83], v[84:85], v[100:101] op_sel_hi:[1,0]
	v_exp_f32_e32 v82, v82
	v_exp_f32_e32 v83, v83
	v_pk_mul_f32 v[92:93], v[8:9], v[92:93] op_sel_hi:[0,1]
	v_pk_mul_f32 v[92:93], v[96:97], v[92:93]
	v_add_f32_e32 v82, 1.0, v82
	v_add_f32_e32 v83, 1.0, v83
	v_rcp_f32_e32 v82, v82
	v_rcp_f32_e32 v83, v83
	v_cvt_pk_bf16_f32 v84, v86, v87
	v_pk_mul_f32 v[82:83], v[8:9], v[82:83] op_sel_hi:[0,1]
	v_or_b32_e32 v8, 32, v142
	v_pk_mul_f32 v[88:89], v[88:89], v[82:83]
	v_mad_i64_i32 v[86:87], s[16:17], v8, s66, v[114:115]
	v_cvt_pk_bf16_f32 v82, v90, v91
	v_cvt_pk_bf16_f32 v83, v92, v93
	v_cvt_pk_bf16_f32 v85, v88, v89
	v_lshl_add_u64 v[86:87], v[86:87], 0, v[116:117]
	v_mov_b32_e32 v8, v153
	global_store_dwordx4 v[86:87], v[82:85], off
	s_nop 1
	v_lshlrev_b64 v[82:83], s4, v[8:9]
	v_min_u32_e32 v8, 1, v82
	v_or_b32_e32 v8, v83, v8
	v_cvt_f32_u32_e32 v8, v8
	v_cvt_f32_u32_e32 v82, v152
	v_ldexp_f32 v8, v8, s5
	v_fmac_f32_e32 v8, 0x2f800000, v82
	v_fmamk_f32 v8, v8, 0x3a000000, v183
	v_rsq_f32_e32 v82, v8
	s_nop 0
	v_mul_f32_e32 v84, 0xbfb8aa3b, v82
	v_mul_f32_e32 v8, v82, v82
	v_pk_mul_f32 v[82:83], v[74:75], v[84:85] op_sel_hi:[1,0]
	v_exp_f32_e32 v82, v82
	v_exp_f32_e32 v83, v83
	v_pk_mul_f32 v[74:75], v[74:75], v[78:79]
	v_mul_f32_e32 v76, v76, v84
	v_add_f32_e32 v82, 1.0, v82
	v_add_f32_e32 v83, 1.0, v83
	v_rcp_f32_e32 v82, v82
	v_rcp_f32_e32 v83, v83
	v_mul_f32_e32 v77, v77, v84
	v_exp_f32_e32 v76, v76
	v_exp_f32_e32 v77, v77
	v_pk_mul_f32 v[78:79], v[8:9], v[82:83] op_sel_hi:[0,1]
	v_pk_mul_f32 v[74:75], v[74:75], v[78:79]
	v_pk_mul_f32 v[78:79], v[66:67], v[84:85] op_sel_hi:[1,0]
	v_exp_f32_e32 v78, v78
	v_exp_f32_e32 v79, v79
	v_pk_mul_f32 v[66:67], v[66:67], v[70:71]
	v_add_f32_e32 v76, 1.0, v76
	v_add_f32_e32 v78, 1.0, v78
	v_add_f32_e32 v79, 1.0, v79
	v_rcp_f32_e32 v78, v78
	v_rcp_f32_e32 v79, v79
	v_add_f32_e32 v77, 1.0, v77
	v_rcp_f32_e32 v76, v76
	v_rcp_f32_e32 v77, v77
	v_pk_mul_f32 v[70:71], v[8:9], v[78:79] op_sel_hi:[0,1]
	v_pk_mul_f32 v[70:71], v[66:67], v[70:71]
	v_pk_mul_f32 v[66:67], v[68:69], v[84:85] op_sel_hi:[1,0]
	v_exp_f32_e32 v66, v66
	v_exp_f32_e32 v67, v67
	v_pk_mul_f32 v[76:77], v[8:9], v[76:77] op_sel_hi:[0,1]
	v_pk_mul_f32 v[76:77], v[80:81], v[76:77]
	v_add_f32_e32 v66, 1.0, v66
	v_add_f32_e32 v67, 1.0, v67
	v_rcp_f32_e32 v66, v66
	v_rcp_f32_e32 v67, v67
	v_cvt_pk_bf16_f32 v68, v70, v71
	v_pk_mul_f32 v[66:67], v[8:9], v[66:67] op_sel_hi:[0,1]
	v_or_b32_e32 v8, 48, v142
	v_pk_mul_f32 v[72:73], v[72:73], v[66:67]
	v_mad_i64_i32 v[70:71], s[16:17], v8, s66, v[114:115]
	v_cvt_pk_bf16_f32 v66, v74, v75
	v_cvt_pk_bf16_f32 v67, v76, v77
	v_cvt_pk_bf16_f32 v69, v72, v73
	v_lshl_add_u64 v[70:71], v[70:71], 0, v[116:117]
	v_mov_b32_e32 v8, v151
	global_store_dwordx4 v[70:71], v[66:69], off
	s_nop 1
	v_lshlrev_b64 v[66:67], s4, v[8:9]
	v_min_u32_e32 v8, 1, v66
	v_or_b32_e32 v8, v67, v8
	v_cvt_f32_u32_e32 v8, v8
	v_cvt_f32_u32_e32 v66, v150
	v_ldexp_f32 v8, v8, s5
	v_fmac_f32_e32 v8, 0x2f800000, v66
	v_fmamk_f32 v8, v8, 0x3a000000, v183
	v_rsq_f32_e32 v66, v8
	s_nop 0
	v_mul_f32_e32 v68, 0xbfb8aa3b, v66
	v_mul_f32_e32 v8, v66, v66
	v_pk_mul_f32 v[66:67], v[58:59], v[68:69] op_sel_hi:[1,0]
	v_exp_f32_e32 v66, v66
	v_exp_f32_e32 v67, v67
	v_pk_mul_f32 v[58:59], v[58:59], v[62:63]
	v_mul_f32_e32 v60, v60, v68
	v_add_f32_e32 v66, 1.0, v66
	v_add_f32_e32 v67, 1.0, v67
	v_rcp_f32_e32 v66, v66
	v_rcp_f32_e32 v67, v67
	v_mul_f32_e32 v61, v61, v68
	v_exp_f32_e32 v60, v60
	v_exp_f32_e32 v61, v61
	v_pk_mul_f32 v[62:63], v[8:9], v[66:67] op_sel_hi:[0,1]
	v_pk_mul_f32 v[58:59], v[58:59], v[62:63]
	v_pk_mul_f32 v[62:63], v[50:51], v[68:69] op_sel_hi:[1,0]
	v_exp_f32_e32 v62, v62
	v_exp_f32_e32 v63, v63
	v_pk_mul_f32 v[50:51], v[50:51], v[54:55]
	v_add_f32_e32 v60, 1.0, v60
	v_add_f32_e32 v62, 1.0, v62
	v_add_f32_e32 v63, 1.0, v63
	v_rcp_f32_e32 v62, v62
	v_rcp_f32_e32 v63, v63
	v_add_f32_e32 v61, 1.0, v61
	v_rcp_f32_e32 v60, v60
	v_rcp_f32_e32 v61, v61
	v_pk_mul_f32 v[54:55], v[8:9], v[62:63] op_sel_hi:[0,1]
	v_pk_mul_f32 v[54:55], v[50:51], v[54:55]
	v_pk_mul_f32 v[50:51], v[52:53], v[68:69] op_sel_hi:[1,0]
	v_exp_f32_e32 v50, v50
	v_exp_f32_e32 v51, v51
	v_pk_mul_f32 v[60:61], v[8:9], v[60:61] op_sel_hi:[0,1]
	v_pk_mul_f32 v[60:61], v[64:65], v[60:61]
	v_add_f32_e32 v50, 1.0, v50
	v_add_f32_e32 v51, 1.0, v51
	v_rcp_f32_e32 v50, v50
	v_rcp_f32_e32 v51, v51
	v_cvt_pk_bf16_f32 v52, v54, v55
	v_mad_i64_i32 v[54:55], s[16:17], v143, s66, v[114:115]
	v_pk_mul_f32 v[50:51], v[8:9], v[50:51] op_sel_hi:[0,1]
	v_pk_mul_f32 v[56:57], v[56:57], v[50:51]
	v_cvt_pk_bf16_f32 v50, v58, v59
	v_cvt_pk_bf16_f32 v51, v60, v61
	v_cvt_pk_bf16_f32 v53, v56, v57
	v_lshl_add_u64 v[54:55], v[54:55], 0, v[116:117]
	v_mov_b32_e32 v8, v149
	global_store_dwordx4 v[54:55], v[50:53], off
	s_nop 1
	v_lshlrev_b64 v[50:51], s4, v[8:9]
	v_min_u32_e32 v8, 1, v50
	v_or_b32_e32 v8, v51, v8
	v_cvt_f32_u32_e32 v8, v8
	v_cvt_f32_u32_e32 v50, v148
	v_ldexp_f32 v8, v8, s5
	v_fmac_f32_e32 v8, 0x2f800000, v50
	v_fmamk_f32 v8, v8, 0x3a000000, v183
	v_rsq_f32_e32 v50, v8
	s_nop 0
	v_mul_f32_e32 v52, 0xbfb8aa3b, v50
	v_mul_f32_e32 v8, v50, v50
	v_pk_mul_f32 v[50:51], v[42:43], v[52:53] op_sel_hi:[1,0]
	v_exp_f32_e32 v50, v50
	v_exp_f32_e32 v51, v51
	v_pk_mul_f32 v[42:43], v[42:43], v[46:47]
	v_mul_f32_e32 v44, v44, v52
	v_add_f32_e32 v50, 1.0, v50
	v_add_f32_e32 v51, 1.0, v51
	v_rcp_f32_e32 v50, v50
	v_rcp_f32_e32 v51, v51
	v_mul_f32_e32 v45, v45, v52
	v_exp_f32_e32 v44, v44
	v_exp_f32_e32 v45, v45
	v_pk_mul_f32 v[46:47], v[8:9], v[50:51] op_sel_hi:[0,1]
	v_pk_mul_f32 v[42:43], v[42:43], v[46:47]
	v_pk_mul_f32 v[46:47], v[34:35], v[52:53] op_sel_hi:[1,0]
	v_exp_f32_e32 v46, v46
	v_exp_f32_e32 v47, v47
	v_pk_mul_f32 v[34:35], v[34:35], v[38:39]
	v_add_f32_e32 v44, 1.0, v44
	v_add_f32_e32 v46, 1.0, v46
	v_add_f32_e32 v47, 1.0, v47
	v_rcp_f32_e32 v46, v46
	v_rcp_f32_e32 v47, v47
	v_add_f32_e32 v45, 1.0, v45
	v_rcp_f32_e32 v44, v44
	v_rcp_f32_e32 v45, v45
	v_pk_mul_f32 v[38:39], v[8:9], v[46:47] op_sel_hi:[0,1]
	v_pk_mul_f32 v[38:39], v[34:35], v[38:39]
	v_pk_mul_f32 v[34:35], v[36:37], v[52:53] op_sel_hi:[1,0]
	v_exp_f32_e32 v34, v34
	v_exp_f32_e32 v35, v35
	v_pk_mul_f32 v[44:45], v[8:9], v[44:45] op_sel_hi:[0,1]
	v_pk_mul_f32 v[44:45], v[48:49], v[44:45]
	v_add_f32_e32 v34, 1.0, v34
	v_add_f32_e32 v35, 1.0, v35
	v_rcp_f32_e32 v34, v34
	v_rcp_f32_e32 v35, v35
	v_cvt_pk_bf16_f32 v36, v38, v39
	v_pk_mul_f32 v[34:35], v[8:9], v[34:35] op_sel_hi:[0,1]
	v_add_u32_e32 v8, 0x90, v142
	v_pk_mul_f32 v[40:41], v[40:41], v[34:35]
	v_mad_i64_i32 v[38:39], s[16:17], v8, s66, v[114:115]
	v_cvt_pk_bf16_f32 v34, v42, v43
	v_cvt_pk_bf16_f32 v35, v44, v45
	v_cvt_pk_bf16_f32 v37, v40, v41
	v_lshl_add_u64 v[38:39], v[38:39], 0, v[116:117]
	v_mov_b32_e32 v8, v147
	global_store_dwordx4 v[38:39], v[34:37], off
	s_nop 1
	v_lshlrev_b64 v[34:35], s4, v[8:9]
	v_min_u32_e32 v8, 1, v34
	v_or_b32_e32 v8, v35, v8
	v_cvt_f32_u32_e32 v8, v8
	v_cvt_f32_u32_e32 v34, v146
	v_ldexp_f32 v8, v8, s5
	v_fmac_f32_e32 v8, 0x2f800000, v34
	v_fmamk_f32 v8, v8, 0x3a000000, v183
	v_rsq_f32_e32 v34, v8
	s_nop 0
	v_mul_f32_e32 v36, 0xbfb8aa3b, v34
	v_mul_f32_e32 v8, v34, v34
	v_pk_mul_f32 v[34:35], v[26:27], v[36:37] op_sel_hi:[1,0]
	v_exp_f32_e32 v34, v34
	v_exp_f32_e32 v35, v35
	v_pk_mul_f32 v[26:27], v[26:27], v[30:31]
	v_mul_f32_e32 v28, v28, v36
	v_add_f32_e32 v34, 1.0, v34
	v_add_f32_e32 v35, 1.0, v35
	v_rcp_f32_e32 v34, v34
	v_rcp_f32_e32 v35, v35
	v_mul_f32_e32 v29, v29, v36
	v_exp_f32_e32 v28, v28
	v_exp_f32_e32 v29, v29
	v_pk_mul_f32 v[30:31], v[8:9], v[34:35] op_sel_hi:[0,1]
	v_pk_mul_f32 v[26:27], v[26:27], v[30:31]
	v_pk_mul_f32 v[30:31], v[18:19], v[36:37] op_sel_hi:[1,0]
	v_exp_f32_e32 v30, v30
	v_exp_f32_e32 v31, v31
	v_pk_mul_f32 v[18:19], v[18:19], v[22:23]
	v_add_f32_e32 v28, 1.0, v28
	v_add_f32_e32 v30, 1.0, v30
	v_add_f32_e32 v31, 1.0, v31
	v_rcp_f32_e32 v30, v30
	v_rcp_f32_e32 v31, v31
	v_add_f32_e32 v29, 1.0, v29
	v_rcp_f32_e32 v28, v28
	v_rcp_f32_e32 v29, v29
	v_pk_mul_f32 v[22:23], v[8:9], v[30:31] op_sel_hi:[0,1]
	v_pk_mul_f32 v[22:23], v[18:19], v[22:23]
	v_pk_mul_f32 v[18:19], v[20:21], v[36:37] op_sel_hi:[1,0]
	v_exp_f32_e32 v18, v18
	v_exp_f32_e32 v19, v19
	v_pk_mul_f32 v[28:29], v[8:9], v[28:29] op_sel_hi:[0,1]
	v_pk_mul_f32 v[28:29], v[32:33], v[28:29]
	v_add_f32_e32 v18, 1.0, v18
	v_add_f32_e32 v19, 1.0, v19
	v_rcp_f32_e32 v18, v18
	v_rcp_f32_e32 v19, v19
	v_cvt_pk_bf16_f32 v20, v22, v23
	v_pk_mul_f32 v[18:19], v[8:9], v[18:19] op_sel_hi:[0,1]
	v_add_u32_e32 v8, 0xa0, v142
	v_pk_mul_f32 v[24:25], v[24:25], v[18:19]
	v_mad_i64_i32 v[22:23], s[16:17], v8, s66, v[114:115]
	v_cvt_pk_bf16_f32 v18, v26, v27
	v_cvt_pk_bf16_f32 v19, v28, v29
	v_cvt_pk_bf16_f32 v21, v24, v25
	v_lshl_add_u64 v[22:23], v[22:23], 0, v[116:117]
	v_mov_b32_e32 v8, v145
	global_store_dwordx4 v[22:23], v[18:21], off
	s_nop 1
	v_lshlrev_b64 v[18:19], s4, v[8:9]
	v_min_u32_e32 v8, 1, v18
	v_or_b32_e32 v8, v19, v8
	v_cvt_f32_u32_e32 v8, v8
	v_cvt_f32_u32_e32 v18, v144
	v_ldexp_f32 v8, v8, s5
	v_fmac_f32_e32 v8, 0x2f800000, v18
	v_fmamk_f32 v8, v8, 0x3a000000, v183
	v_rsq_f32_e32 v18, v8
	s_nop 0
	v_mul_f32_e32 v20, 0xbfb8aa3b, v18
	v_mul_f32_e32 v8, v18, v18
	v_pk_mul_f32 v[18:19], v[10:11], v[20:21] op_sel_hi:[1,0]
	v_exp_f32_e32 v18, v18
	v_exp_f32_e32 v19, v19
	v_pk_mul_f32 v[10:11], v[10:11], v[14:15]
	v_mul_f32_e32 v12, v12, v20
	v_add_f32_e32 v18, 1.0, v18
	v_add_f32_e32 v19, 1.0, v19
	v_rcp_f32_e32 v18, v18
	v_rcp_f32_e32 v19, v19
	v_mul_f32_e32 v13, v13, v20
	v_exp_f32_e32 v12, v12
	v_exp_f32_e32 v13, v13
	v_pk_mul_f32 v[14:15], v[8:9], v[18:19] op_sel_hi:[0,1]
	v_pk_mul_f32 v[10:11], v[10:11], v[14:15]
	v_pk_mul_f32 v[14:15], v[4:5], v[20:21] op_sel_hi:[1,0]
	v_exp_f32_e32 v14, v14
	v_exp_f32_e32 v15, v15
	v_add_f32_e32 v12, 1.0, v12
	v_add_f32_e32 v13, 1.0, v13
	v_add_f32_e32 v14, 1.0, v14
	v_add_f32_e32 v15, 1.0, v15
	v_rcp_f32_e32 v14, v14
	v_rcp_f32_e32 v15, v15
	v_rcp_f32_e32 v12, v12
	v_rcp_f32_e32 v13, v13
	v_pk_mul_f32 v[4:5], v[8:9], v[14:15] op_sel_hi:[0,1]
	v_pk_mul_f32 v[4:5], v[0:1], v[4:5]
	v_pk_mul_f32 v[0:1], v[6:7], v[20:21] op_sel_hi:[1,0]
	v_exp_f32_e32 v0, v0
	v_exp_f32_e32 v1, v1
	v_pk_mul_f32 v[12:13], v[8:9], v[12:13] op_sel_hi:[0,1]
	v_pk_mul_f32 v[12:13], v[16:17], v[12:13]
	v_add_f32_e32 v0, 1.0, v0
	v_add_f32_e32 v1, 1.0, v1
	v_rcp_f32_e32 v0, v0
	v_rcp_f32_e32 v1, v1
	s_nop 0
	v_pk_mul_f32 v[0:1], v[8:9], v[0:1] op_sel_hi:[0,1]
	v_add_u32_e32 v8, 0xb0, v142
	v_pk_mul_f32 v[6:7], v[2:3], v[0:1]
	v_cvt_pk_bf16_f32 v2, v4, v5
	v_mad_i64_i32 v[4:5], s[4:5], v8, s66, v[114:115]
	v_cvt_pk_bf16_f32 v0, v10, v11
	v_cvt_pk_bf16_f32 v1, v12, v13
	v_cvt_pk_bf16_f32 v3, v6, v7
	v_lshl_add_u64 v[4:5], v[4:5], 0, v[116:117]
	global_store_dwordx4 v[4:5], v[0:3], off
	s_mov_b64 s[4:5], -1
	s_cbranch_vccnz .LBB0_939
	s_andn2_b64 vcc, exec, s[18:19]
	s_cbranch_vccnz .LBB0_938
	s_barrier
	s_branch .LBB0_938
